# grid barrier: follower workgroups poll the top-level generation word directly (skips the per-XCD release hop); plus in-proj slack late start
# baseline (speedup 1.0000x reference)
; __device__ __forceinline__ unsigned xb_ld(unsigned* p)              { return __hip_atomic_load(p, __ATOMIC_RELAXED, __HIP_MEMORY_SCOPE_AGENT); }
; __device__ __forceinline__ unsigned xb_add(unsigned* p, unsigned v) { return __hip_atomic_fetch_add(p, v, __ATOMIC_RELAXED, __HIP_MEMORY_SCOPE_AGENT); }
; #define XB_SPIN(cond, bar) do { unsigned _sp = 0; while (cond) { __builtin_amdgcn_s_sleep(1); \
;     if ((++_sp & 255u) == 0u) { if (xb_ld(&(bar)[XB_TMO])) break; if (_sp > XB_SPIN_CAP) { atomicAdd(&(bar)[XB_TMO], 1u); break; } } } } while (0)
; __device__ __forceinline__ void xcd_barrier(const XcdBarrier& b) {
;     ...
;         const unsigned old = xb_add(&bar[XB_XSUB(b.x)], 1u);
;         const unsigned gen = old / nloc;
;         if (old + 1u == (gen + 1u) * nloc) {
;             __builtin_amdgcn_fence(__ATOMIC_RELEASE, "agent");
;             asm volatile("s_waitcnt vmcnt(0)" ::: "memory");
;             const unsigned og = xb_add(&bar[XB_TOP], 1u);
;             const unsigned tg = og / nx;
;             if (og + 1u == (tg + 1u) * nx) xb_add(&bar[XB_TOPGEN], 1u);
;             else XB_SPIN(xb_ld(&bar[XB_TOPGEN]) == tg, bar);
;             __builtin_amdgcn_fence(__ATOMIC_ACQUIRE, "agent");
;             xb_add(&bar[XB_XGEN(b.x)], 1u);
;             asm volatile("s_waitcnt vmcnt(0)" ::: "memory");
;         } else {
;             XB_SPIN(xb_ld(&bar[XB_XGEN(b.x)]) == gen, bar);
;             __builtin_amdgcn_fence(__ATOMIC_ACQUIRE, "agent");
;             asm volatile("s_waitcnt vmcnt(0)" ::: "memory");
;         }
.LBB0_148:
	global_atomic_add v3, v[130:131], v176, off sc0
	v_cvt_f32_u32_e32 v1, v2
	v_sub_u32_e32 v4, 0, v2
	v_rcp_iflag_f32_e32 v1, v1
	s_nop 0
	v_mul_f32_e32 v1, 0x4f7ffffe, v1
	v_cvt_u32_f32_e32 v1, v1
	v_mul_lo_u32 v4, v4, v1
	v_mul_hi_u32 v4, v1, v4
	v_add_u32_e32 v1, v1, v4
	s_waitcnt vmcnt(0)
	v_mul_hi_u32 v1, v3, v1
	v_mul_lo_u32 v4, v1, v2
	v_sub_u32_e32 v4, v3, v4
	v_add_u32_e32 v5, 1, v1
	v_sub_u32_e32 v6, v4, v2
	v_cmp_ge_u32_e32 vcc, v4, v2
	v_add_u32_e32 v3, 1, v3
	s_nop 0
	v_cndmask_b32_e32 v1, v1, v5, vcc
	v_cndmask_b32_e32 v4, v4, v6, vcc
	v_add_u32_e32 v5, 1, v1
	v_cmp_ge_u32_e32 vcc, v4, v2
	s_nop 1
	v_cndmask_b32_e32 v1, v1, v5, vcc
	v_mul_lo_u32 v4, v2, v1
	v_add_u32_e32 v2, v4, v2
	v_cmp_ne_u32_e32 vcc, v3, v2
	s_and_saveexec_b64 s[6:7], vcc
	s_xor_b64 s[38:39], exec, s[6:7]
	s_cbranch_execz .LBB0_162
	v_readlane_b32 s100, v243, 37
	v_readlane_b32 s101, v243, 38
	s_waitcnt lgkmcnt(0)
	buffer_inv sc1
	s_nop 2
	global_load_dword v0, v8, s[100:101] sc1
	s_waitcnt vmcnt(0)
	v_cmp_eq_u32_e32 vcc, v0, v1
	s_and_saveexec_b64 s[40:41], vcc
	s_cbranch_execz .LBB0_161
	s_mov_b32 s2, 1
	s_mov_b64 s[42:43], 0
	s_branch .LBB0_152

; __device__ __forceinline__ unsigned xb_ld(unsigned* p)              { return __hip_atomic_load(p, __ATOMIC_RELAXED, __HIP_MEMORY_SCOPE_AGENT); }
; #define XB_SPIN(cond, bar) do { unsigned _sp = 0; while (cond) { __builtin_amdgcn_s_sleep(1); \
;     if ((++_sp & 255u) == 0u) { if (xb_ld(&(bar)[XB_TMO])) break; if (_sp > XB_SPIN_CAP) { atomicAdd(&(bar)[XB_TMO], 1u); break; } } } } while (0)
; __device__ __forceinline__ void xcd_barrier(const XcdBarrier& b) {
;     ...
;             XB_SPIN(xb_ld(&bar[XB_XGEN(b.x)]) == gen, bar);
.LBB0_156:
	global_load_dword v0, v8, s[100:101] sc1
	s_add_i32 s2, s2, 1
	s_mov_b64 s[72:73], -1
	s_waitcnt vmcnt(0)
	v_cmp_ne_u32_e32 vcc, v0, v1
	s_orn2_b64 s[70:71], vcc, exec
	s_branch .LBB0_151

; __device__ __forceinline__ unsigned xb_ld(unsigned* p)              { return __hip_atomic_load(p, __ATOMIC_RELAXED, __HIP_MEMORY_SCOPE_AGENT); }
; __device__ __forceinline__ unsigned xb_add(unsigned* p, unsigned v) { return __hip_atomic_fetch_add(p, v, __ATOMIC_RELAXED, __HIP_MEMORY_SCOPE_AGENT); }
; #define XB_SPIN(cond, bar) do { unsigned _sp = 0; while (cond) { __builtin_amdgcn_s_sleep(1); \
;     if ((++_sp & 255u) == 0u) { if (xb_ld(&(bar)[XB_TMO])) break; if (_sp > XB_SPIN_CAP) { atomicAdd(&(bar)[XB_TMO], 1u); break; } } } } while (0)
; __device__ __forceinline__ void xcd_barrier(const XcdBarrier& b) {
;     ...
;         const unsigned old = xb_add(&bar[XB_XSUB(b.x)], 1u);
;         const unsigned gen = old / nloc;
;         if (old + 1u == (gen + 1u) * nloc) {
;             __builtin_amdgcn_fence(__ATOMIC_RELEASE, "agent");
;             asm volatile("s_waitcnt vmcnt(0)" ::: "memory");
;             const unsigned og = xb_add(&bar[XB_TOP], 1u);
;             const unsigned tg = og / nx;
;             if (og + 1u == (tg + 1u) * nx) xb_add(&bar[XB_TOPGEN], 1u);
;             else XB_SPIN(xb_ld(&bar[XB_TOPGEN]) == tg, bar);
;             __builtin_amdgcn_fence(__ATOMIC_ACQUIRE, "agent");
;             xb_add(&bar[XB_XGEN(b.x)], 1u);
;             asm volatile("s_waitcnt vmcnt(0)" ::: "memory");
;         } else {
;             XB_SPIN(xb_ld(&bar[XB_XGEN(b.x)]) == gen, bar);
;             __builtin_amdgcn_fence(__ATOMIC_ACQUIRE, "agent");
;             asm volatile("s_waitcnt vmcnt(0)" ::: "memory");
;         }
.LBB0_208:
	global_atomic_add v3, v[130:131], v176, off sc0
	v_cvt_f32_u32_e32 v1, v2
	v_sub_u32_e32 v4, 0, v2
	v_rcp_iflag_f32_e32 v1, v1
	s_nop 0
	v_mul_f32_e32 v1, 0x4f7ffffe, v1
	v_cvt_u32_f32_e32 v1, v1
	v_mul_lo_u32 v4, v4, v1
	v_mul_hi_u32 v4, v1, v4
	v_add_u32_e32 v1, v1, v4
	s_waitcnt vmcnt(0)
	v_mul_hi_u32 v1, v3, v1
	v_mul_lo_u32 v4, v1, v2
	v_sub_u32_e32 v4, v3, v4
	v_add_u32_e32 v5, 1, v1
	v_cmp_ge_u32_e32 vcc, v4, v2
	v_add_u32_e32 v3, 1, v3
	s_nop 0
	v_cndmask_b32_e32 v1, v1, v5, vcc
	v_sub_u32_e32 v5, v4, v2
	v_cndmask_b32_e32 v4, v4, v5, vcc
	v_add_u32_e32 v5, 1, v1
	v_cmp_ge_u32_e32 vcc, v4, v2
	s_nop 1
	v_cndmask_b32_e32 v1, v1, v5, vcc
	v_mul_lo_u32 v4, v2, v1
	v_add_u32_e32 v2, v4, v2
	v_cmp_ne_u32_e32 vcc, v3, v2
	s_and_saveexec_b64 s[6:7], vcc
	s_xor_b64 s[38:39], exec, s[6:7]
	s_cbranch_execz .LBB0_222
	v_readlane_b32 s100, v243, 37
	v_readlane_b32 s101, v243, 38
	s_waitcnt lgkmcnt(0)
	buffer_inv sc1
	s_nop 2
	global_load_dword v0, v8, s[100:101] sc1
	s_waitcnt vmcnt(0)
	v_cmp_eq_u32_e32 vcc, v0, v1
	s_and_saveexec_b64 s[40:41], vcc
	s_cbranch_execz .LBB0_221
	s_mov_b32 s2, 1
	s_mov_b64 s[42:43], 0
	s_branch .LBB0_212

; __device__ __forceinline__ unsigned xb_ld(unsigned* p)              { return __hip_atomic_load(p, __ATOMIC_RELAXED, __HIP_MEMORY_SCOPE_AGENT); }
; __device__ __forceinline__ unsigned xb_add(unsigned* p, unsigned v) { return __hip_atomic_fetch_add(p, v, __ATOMIC_RELAXED, __HIP_MEMORY_SCOPE_AGENT); }
; #define XB_SPIN(cond, bar) do { unsigned _sp = 0; while (cond) { __builtin_amdgcn_s_sleep(1); \
;     if ((++_sp & 255u) == 0u) { if (xb_ld(&(bar)[XB_TMO])) break; if (_sp > XB_SPIN_CAP) { atomicAdd(&(bar)[XB_TMO], 1u); break; } } } } while (0)
; __device__ __forceinline__ void xcd_barrier(const XcdBarrier& b) {
;     ...
;         const unsigned old = xb_add(&bar[XB_XSUB(b.x)], 1u);
;         const unsigned gen = old / nloc;
;         if (old + 1u == (gen + 1u) * nloc) {
;             __builtin_amdgcn_fence(__ATOMIC_RELEASE, "agent");
;             asm volatile("s_waitcnt vmcnt(0)" ::: "memory");
;             const unsigned og = xb_add(&bar[XB_TOP], 1u);
;             const unsigned tg = og / nx;
;             if (og + 1u == (tg + 1u) * nx) xb_add(&bar[XB_TOPGEN], 1u);
;             else XB_SPIN(xb_ld(&bar[XB_TOPGEN]) == tg, bar);
;             __builtin_amdgcn_fence(__ATOMIC_ACQUIRE, "agent");
;             xb_add(&bar[XB_XGEN(b.x)], 1u);
;             asm volatile("s_waitcnt vmcnt(0)" ::: "memory");
;         } else {
;             XB_SPIN(xb_ld(&bar[XB_XGEN(b.x)]) == gen, bar);
;             __builtin_amdgcn_fence(__ATOMIC_ACQUIRE, "agent");
;             asm volatile("s_waitcnt vmcnt(0)" ::: "memory");
;         }
.LBB0_536:
	global_atomic_add v3, v[130:131], v176, off sc0
	v_cvt_f32_u32_e32 v1, v2
	v_sub_u32_e32 v4, 0, v2
	v_rcp_iflag_f32_e32 v1, v1
	s_nop 0
	v_mul_f32_e32 v1, 0x4f7ffffe, v1
	v_cvt_u32_f32_e32 v1, v1
	v_mul_lo_u32 v4, v4, v1
	v_mul_hi_u32 v4, v1, v4
	v_add_u32_e32 v1, v1, v4
	s_waitcnt vmcnt(0)
	v_mul_hi_u32 v1, v3, v1
	v_mul_lo_u32 v4, v1, v2
	v_sub_u32_e32 v4, v3, v4
	v_add_u32_e32 v5, 1, v1
	v_cmp_ge_u32_e32 vcc, v4, v2
	v_add_u32_e32 v3, 1, v3
	s_nop 0
	v_cndmask_b32_e32 v1, v1, v5, vcc
	v_sub_u32_e32 v5, v4, v2
	v_cndmask_b32_e32 v4, v4, v5, vcc
	v_add_u32_e32 v5, 1, v1
	v_cmp_ge_u32_e32 vcc, v4, v2
	s_nop 1
	v_cndmask_b32_e32 v1, v1, v5, vcc
	v_mul_lo_u32 v4, v2, v1
	v_add_u32_e32 v2, v4, v2
	v_cmp_ne_u32_e32 vcc, v3, v2
	s_and_saveexec_b64 s[6:7], vcc
	s_xor_b64 s[38:39], exec, s[6:7]
	s_cbranch_execz .LBB0_550
	v_readlane_b32 s100, v243, 37
	v_readlane_b32 s101, v243, 38
	s_waitcnt lgkmcnt(0)
	buffer_inv sc1
	s_nop 2
	global_load_dword v0, v8, s[100:101] sc1
	s_waitcnt vmcnt(0)
	v_cmp_eq_u32_e32 vcc, v0, v1
	s_and_saveexec_b64 s[40:41], vcc
	s_cbranch_execz .LBB0_549
	s_mov_b32 s6, 1
	s_mov_b64 s[42:43], 0
	s_branch .LBB0_540

; __device__ __forceinline__ unsigned xb_ld(unsigned* p)              { return __hip_atomic_load(p, __ATOMIC_RELAXED, __HIP_MEMORY_SCOPE_AGENT); }
; #define XB_SPIN(cond, bar) do { unsigned _sp = 0; while (cond) { __builtin_amdgcn_s_sleep(1); \
;     if ((++_sp & 255u) == 0u) { if (xb_ld(&(bar)[XB_TMO])) break; if (_sp > XB_SPIN_CAP) { atomicAdd(&(bar)[XB_TMO], 1u); break; } } } } while (0)
; __device__ __forceinline__ void xcd_barrier(const XcdBarrier& b) {
;     ...
;             XB_SPIN(xb_ld(&bar[XB_XGEN(b.x)]) == gen, bar);
.LBB0_544:
	global_load_dword v0, v8, s[100:101] sc1
	s_add_i32 s6, s6, 1
	s_mov_b64 s[72:73], -1
	s_waitcnt vmcnt(0)
	v_cmp_ne_u32_e32 vcc, v0, v1
	s_orn2_b64 s[70:71], vcc, exec
	s_branch .LBB0_539
